# removed redundant first accumulator-zeroing block (128 v_mov per unit) in 7 GEMM instances
# speedup vs baseline: 1.0100x; 1.0100x over previous
; template <class Epi, class Sched, bool ALIGN_EPI = false, bool SP2 = false>
; __device__ __forceinline__ void gemm_phase(PG8_LAS unsigned char* lds, const Gemm g, const Sched& S, const Epi& E) {
;     ...
;         for (int t = 0; t < nt; t += 2) {
;     ...
; #pragma unroll
;         for (int a = 0; a < 2; ++a)
; #pragma unroll
;             for (int b = 0; b < 2; ++b)
; #pragma unroll
;                 for (int m = 0; m < 4; ++m)
; #pragma unroll
;                     for (int n = 0; n < 2; ++n) acc[a][b][m][n] = (f32x4){0.f, 0.f, 0.f, 0.f};
;         cur = nxt; cA = nA; cB = nB; ++ui;
.LBB0_354:
	s_andn2_b64 vcc, exec, s[22:23]
	s_waitcnt lgkmcnt(0)
	s_cbranch_vccnz .LBB0_357
	s_add_u32 s4, s4, 0x80
	s_addc_u32 s5, s5, 0
	s_add_u32 s11, s6, 0x100
	v_mov_b32_e32 v0, 0
	s_addc_u32 s16, s7, 0
	s_mov_b32 s6, 0
	v_mov_b32_e32 v1, v0
	v_mov_b32_e32 v2, v0
	v_mov_b32_e32 v3, v0
	v_mov_b32_e32 v8, v0
	v_mov_b32_e32 v9, v0
	v_mov_b32_e32 v10, v0
	v_mov_b32_e32 v11, v0
	v_mov_b32_e32 v16, v0
	v_mov_b32_e32 v17, v0
	v_mov_b32_e32 v18, v0
	v_mov_b32_e32 v19, v0
	v_mov_b32_e32 v24, v0
	v_mov_b32_e32 v25, v0
	v_mov_b32_e32 v26, v0
	v_mov_b32_e32 v27, v0
	v_mov_b32_e32 v32, v0
	v_mov_b32_e32 v33, v0
	v_mov_b32_e32 v34, v0
	v_mov_b32_e32 v35, v0
	v_mov_b32_e32 v40, v0
	v_mov_b32_e32 v41, v0
	v_mov_b32_e32 v42, v0
	v_mov_b32_e32 v43, v0
	v_mov_b32_e32 v48, v0
	v_mov_b32_e32 v49, v0
	v_mov_b32_e32 v50, v0
	v_mov_b32_e32 v51, v0
	v_mov_b32_e32 v56, v0
	v_mov_b32_e32 v57, v0
	v_mov_b32_e32 v58, v0
	v_mov_b32_e32 v59, v0
	v_mov_b32_e32 v4, v0
	v_mov_b32_e32 v5, v0
	v_mov_b32_e32 v6, v0
	v_mov_b32_e32 v7, v0
	v_mov_b32_e32 v12, v0
	v_mov_b32_e32 v13, v0
	v_mov_b32_e32 v14, v0
	v_mov_b32_e32 v15, v0
	v_mov_b32_e32 v20, v0
	v_mov_b32_e32 v21, v0
	v_mov_b32_e32 v22, v0
	v_mov_b32_e32 v23, v0
	v_mov_b32_e32 v28, v0
	v_mov_b32_e32 v29, v0
	v_mov_b32_e32 v30, v0
	v_mov_b32_e32 v31, v0
	v_mov_b32_e32 v36, v0
	v_mov_b32_e32 v37, v0
	v_mov_b32_e32 v38, v0
	v_mov_b32_e32 v39, v0
	v_mov_b32_e32 v44, v0
	v_mov_b32_e32 v45, v0
	v_mov_b32_e32 v46, v0
	v_mov_b32_e32 v47, v0
	v_mov_b32_e32 v52, v0
	v_mov_b32_e32 v53, v0
	v_mov_b32_e32 v54, v0
	v_mov_b32_e32 v55, v0
	v_mov_b32_e32 v60, v0
	v_mov_b32_e32 v61, v0
	v_mov_b32_e32 v62, v0
	v_mov_b32_e32 v63, v0
	v_mov_b32_e32 v64, v0
	v_mov_b32_e32 v65, v0
	v_mov_b32_e32 v66, v0
	v_mov_b32_e32 v67, v0
	v_mov_b32_e32 v72, v0
	v_mov_b32_e32 v73, v0
	v_mov_b32_e32 v74, v0
	v_mov_b32_e32 v75, v0
	v_mov_b32_e32 v80, v0
	v_mov_b32_e32 v81, v0
	v_mov_b32_e32 v82, v0
	v_mov_b32_e32 v83, v0
	v_mov_b32_e32 v88, v0
	v_mov_b32_e32 v89, v0
	v_mov_b32_e32 v90, v0
	v_mov_b32_e32 v91, v0
	v_mov_b32_e32 v96, v0
	v_mov_b32_e32 v97, v0
	v_mov_b32_e32 v98, v0
	v_mov_b32_e32 v99, v0
	v_mov_b32_e32 v104, v0
	v_mov_b32_e32 v105, v0
	v_mov_b32_e32 v106, v0
	v_mov_b32_e32 v107, v0
	v_mov_b32_e32 v112, v0
	v_mov_b32_e32 v113, v0
	v_mov_b32_e32 v114, v0
	v_mov_b32_e32 v115, v0
	v_mov_b32_e32 v124, v0
	v_mov_b32_e32 v125, v0
	v_mov_b32_e32 v126, v0
	v_mov_b32_e32 v127, v0
	v_mov_b32_e32 v68, v0
	v_mov_b32_e32 v69, v0
	v_mov_b32_e32 v70, v0
	v_mov_b32_e32 v71, v0
	v_mov_b32_e32 v76, v0
	v_mov_b32_e32 v77, v0
	v_mov_b32_e32 v78, v0
	v_mov_b32_e32 v79, v0
	v_mov_b32_e32 v84, v0
	v_mov_b32_e32 v85, v0
	v_mov_b32_e32 v86, v0
	v_mov_b32_e32 v87, v0
	v_mov_b32_e32 v92, v0
	v_mov_b32_e32 v93, v0
	v_mov_b32_e32 v94, v0
	v_mov_b32_e32 v95, v0
	v_mov_b32_e32 v100, v0
	v_mov_b32_e32 v101, v0
	v_mov_b32_e32 v102, v0
	v_mov_b32_e32 v103, v0
	v_mov_b32_e32 v108, v0
	v_mov_b32_e32 v109, v0
	v_mov_b32_e32 v110, v0
	v_mov_b32_e32 v111, v0
	v_mov_b32_e32 v116, v0
	v_mov_b32_e32 v117, v0
	v_mov_b32_e32 v118, v0
	v_mov_b32_e32 v119, v0
	v_mov_b32_e32 v120, v0
	v_mov_b32_e32 v121, v0
	v_mov_b32_e32 v122, v0
	v_mov_b32_e32 v123, v0

; template <class Epi, class Sched, bool ALIGN_EPI = false, bool SP2 = false>
; __device__ __forceinline__ void gemm_phase(PG8_LAS unsigned char* lds, const Gemm g, const Sched& S, const Epi& E) {
;     ...
;         for (int t = 0; t < nt; t += 2) {
;     ...
; #pragma unroll
;         for (int a = 0; a < 2; ++a)
; #pragma unroll
;             for (int b = 0; b < 2; ++b)
; #pragma unroll
;                 for (int m = 0; m < 4; ++m)
; #pragma unroll
;                     for (int n = 0; n < 2; ++n) acc[a][b][m][n] = (f32x4){0.f, 0.f, 0.f, 0.f};
;         cur = nxt; cA = nA; cB = nB; ++ui;
.LBB0_710:
	s_andn2_b64 vcc, exec, s[18:19]
	s_cbranch_vccnz .LBB0_713
	s_add_u32 s6, s6, 0x80
	s_addc_u32 s7, s7, 0
	s_add_u32 s58, s30, 0x100
	v_mov_b32_e32 v4, 0
	s_addc_u32 s59, s31, 0
	s_mov_b32 s30, 0
	v_mov_b32_e32 v5, v4
	v_mov_b32_e32 v6, v4
	v_mov_b32_e32 v7, v4
	v_mov_b32_e32 v0, v4
	v_mov_b32_e32 v1, v4
	v_mov_b32_e32 v2, v4
	v_mov_b32_e32 v3, v4
	v_mov_b32_e32 v16, v4
	v_mov_b32_e32 v17, v4
	v_mov_b32_e32 v18, v4
	v_mov_b32_e32 v19, v4
	v_mov_b32_e32 v20, v4
	v_mov_b32_e32 v21, v4
	v_mov_b32_e32 v22, v4
	v_mov_b32_e32 v23, v4
	v_mov_b32_e32 v32, v4
	v_mov_b32_e32 v33, v4
	v_mov_b32_e32 v34, v4
	v_mov_b32_e32 v35, v4
	v_mov_b32_e32 v36, v4
	v_mov_b32_e32 v37, v4
	v_mov_b32_e32 v38, v4
	v_mov_b32_e32 v39, v4
	v_mov_b32_e32 v48, v4
	v_mov_b32_e32 v49, v4
	v_mov_b32_e32 v50, v4
	v_mov_b32_e32 v51, v4
	v_mov_b32_e32 v52, v4
	v_mov_b32_e32 v53, v4
	v_mov_b32_e32 v54, v4
	v_mov_b32_e32 v55, v4
	v_mov_b32_e32 v8, v4
	v_mov_b32_e32 v9, v4
	v_mov_b32_e32 v10, v4
	v_mov_b32_e32 v11, v4
	v_mov_b32_e32 v12, v4
	v_mov_b32_e32 v13, v4
	v_mov_b32_e32 v14, v4
	v_mov_b32_e32 v15, v4
	v_mov_b32_e32 v24, v4
	v_mov_b32_e32 v25, v4
	v_mov_b32_e32 v26, v4
	v_mov_b32_e32 v27, v4
	v_mov_b32_e32 v28, v4
	v_mov_b32_e32 v29, v4
	v_mov_b32_e32 v30, v4
	v_mov_b32_e32 v31, v4
	v_mov_b32_e32 v40, v4
	v_mov_b32_e32 v41, v4
	v_mov_b32_e32 v42, v4
	v_mov_b32_e32 v43, v4
	v_mov_b32_e32 v44, v4
	v_mov_b32_e32 v45, v4
	v_mov_b32_e32 v46, v4
	v_mov_b32_e32 v47, v4
	v_mov_b32_e32 v56, v4
	v_mov_b32_e32 v57, v4
	v_mov_b32_e32 v58, v4
	v_mov_b32_e32 v59, v4
	v_mov_b32_e32 v60, v4
	v_mov_b32_e32 v61, v4
	v_mov_b32_e32 v62, v4
	v_mov_b32_e32 v63, v4
	v_mov_b32_e32 v64, v4
	v_mov_b32_e32 v65, v4
	v_mov_b32_e32 v66, v4
	v_mov_b32_e32 v67, v4
	v_mov_b32_e32 v68, v4
	v_mov_b32_e32 v69, v4
	v_mov_b32_e32 v70, v4
	v_mov_b32_e32 v71, v4
	v_mov_b32_e32 v80, v4
	v_mov_b32_e32 v81, v4
	v_mov_b32_e32 v82, v4
	v_mov_b32_e32 v83, v4
	v_mov_b32_e32 v84, v4
	v_mov_b32_e32 v85, v4
	v_mov_b32_e32 v86, v4
	v_mov_b32_e32 v87, v4
	v_mov_b32_e32 v96, v4
	v_mov_b32_e32 v97, v4
	v_mov_b32_e32 v98, v4
	v_mov_b32_e32 v99, v4
	v_mov_b32_e32 v100, v4
	v_mov_b32_e32 v101, v4
	v_mov_b32_e32 v102, v4
	v_mov_b32_e32 v103, v4
	v_mov_b32_e32 v112, v4
	v_mov_b32_e32 v113, v4
	v_mov_b32_e32 v114, v4
	v_mov_b32_e32 v115, v4
	v_mov_b32_e32 v116, v4
	v_mov_b32_e32 v117, v4
	v_mov_b32_e32 v118, v4
	v_mov_b32_e32 v119, v4
	v_mov_b32_e32 v72, v4
	v_mov_b32_e32 v73, v4
	v_mov_b32_e32 v74, v4
	v_mov_b32_e32 v75, v4
	v_mov_b32_e32 v76, v4
	v_mov_b32_e32 v77, v4
	v_mov_b32_e32 v78, v4
	v_mov_b32_e32 v79, v4
	v_mov_b32_e32 v88, v4
	v_mov_b32_e32 v89, v4
	v_mov_b32_e32 v90, v4
	v_mov_b32_e32 v91, v4
	v_mov_b32_e32 v92, v4
	v_mov_b32_e32 v93, v4
	v_mov_b32_e32 v94, v4
	v_mov_b32_e32 v95, v4
	v_mov_b32_e32 v104, v4
	v_mov_b32_e32 v105, v4
	v_mov_b32_e32 v106, v4
	v_mov_b32_e32 v107, v4
	v_mov_b32_e32 v108, v4
	v_mov_b32_e32 v109, v4
	v_mov_b32_e32 v110, v4
	v_mov_b32_e32 v111, v4
	v_mov_b32_e32 v124, v4
	v_mov_b32_e32 v125, v4
	v_mov_b32_e32 v126, v4
	v_mov_b32_e32 v127, v4
	v_mov_b32_e32 v120, v4
	v_mov_b32_e32 v121, v4
	v_mov_b32_e32 v122, v4
	v_mov_b32_e32 v123, v4

; template <class Epi, class Sched, bool ALIGN_EPI = false, bool SP2 = false>
; __device__ __forceinline__ void gemm_phase(PG8_LAS unsigned char* lds, const Gemm g, const Sched& S, const Epi& E) {
;     ...
;         for (int t = 0; t < nt; t += 2) {
;     ...
; #pragma unroll
;         for (int a = 0; a < 2; ++a)
; #pragma unroll
;             for (int b = 0; b < 2; ++b)
; #pragma unroll
;                 for (int m = 0; m < 4; ++m)
; #pragma unroll
;                     for (int n = 0; n < 2; ++n) acc[a][b][m][n] = (f32x4){0.f, 0.f, 0.f, 0.f};
;         cur = nxt; cA = nA; cB = nB; ++ui;
.LBB0_773:
	s_andn2_b64 vcc, exec, s[16:17]
	s_cbranch_vccnz .LBB0_776
	s_add_u32 s10, s10, 0x80
	s_addc_u32 s11, s11, 0
	s_add_u32 s55, s30, 0x100
	v_mov_b32_e32 v4, 0
	s_addc_u32 s56, s31, 0
	s_mov_b32 s30, 0
	v_mov_b32_e32 v5, v4
	v_mov_b32_e32 v6, v4
	v_mov_b32_e32 v7, v4
	v_mov_b32_e32 v12, v4
	v_mov_b32_e32 v13, v4
	v_mov_b32_e32 v14, v4
	v_mov_b32_e32 v15, v4
	v_mov_b32_e32 v20, v4
	v_mov_b32_e32 v21, v4
	v_mov_b32_e32 v22, v4
	v_mov_b32_e32 v23, v4
	v_mov_b32_e32 v28, v4
	v_mov_b32_e32 v29, v4
	v_mov_b32_e32 v30, v4
	v_mov_b32_e32 v31, v4
	v_mov_b32_e32 v36, v4
	v_mov_b32_e32 v37, v4
	v_mov_b32_e32 v38, v4
	v_mov_b32_e32 v39, v4
	v_mov_b32_e32 v44, v4
	v_mov_b32_e32 v45, v4
	v_mov_b32_e32 v46, v4
	v_mov_b32_e32 v47, v4
	v_mov_b32_e32 v52, v4
	v_mov_b32_e32 v53, v4
	v_mov_b32_e32 v54, v4
	v_mov_b32_e32 v55, v4
	v_mov_b32_e32 v60, v4
	v_mov_b32_e32 v61, v4
	v_mov_b32_e32 v62, v4
	v_mov_b32_e32 v63, v4
	v_mov_b32_e32 v0, v4
	v_mov_b32_e32 v1, v4
	v_mov_b32_e32 v2, v4
	v_mov_b32_e32 v3, v4
	v_mov_b32_e32 v8, v4
	v_mov_b32_e32 v9, v4
	v_mov_b32_e32 v10, v4
	v_mov_b32_e32 v11, v4
	v_mov_b32_e32 v16, v4
	v_mov_b32_e32 v17, v4
	v_mov_b32_e32 v18, v4
	v_mov_b32_e32 v19, v4
	v_mov_b32_e32 v24, v4
	v_mov_b32_e32 v25, v4
	v_mov_b32_e32 v26, v4
	v_mov_b32_e32 v27, v4
	v_mov_b32_e32 v32, v4
	v_mov_b32_e32 v33, v4
	v_mov_b32_e32 v34, v4
	v_mov_b32_e32 v35, v4
	v_mov_b32_e32 v40, v4
	v_mov_b32_e32 v41, v4
	v_mov_b32_e32 v42, v4
	v_mov_b32_e32 v43, v4
	v_mov_b32_e32 v48, v4
	v_mov_b32_e32 v49, v4
	v_mov_b32_e32 v50, v4
	v_mov_b32_e32 v51, v4
	v_mov_b32_e32 v56, v4
	v_mov_b32_e32 v57, v4
	v_mov_b32_e32 v58, v4
	v_mov_b32_e32 v59, v4
	v_mov_b32_e32 v68, v4
	v_mov_b32_e32 v69, v4
	v_mov_b32_e32 v70, v4
	v_mov_b32_e32 v71, v4
	v_mov_b32_e32 v76, v4
	v_mov_b32_e32 v77, v4
	v_mov_b32_e32 v78, v4
	v_mov_b32_e32 v79, v4
	v_mov_b32_e32 v108, v4
	v_mov_b32_e32 v109, v4
	v_mov_b32_e32 v110, v4
	v_mov_b32_e32 v111, v4
	v_mov_b32_e32 v116, v4
	v_mov_b32_e32 v117, v4
	v_mov_b32_e32 v118, v4
	v_mov_b32_e32 v119, v4
	v_mov_b32_e32 v124, v4
	v_mov_b32_e32 v125, v4
	v_mov_b32_e32 v126, v4
	v_mov_b32_e32 v127, v4
	v_mov_b32_e32 v132, v4
	v_mov_b32_e32 v133, v4
	v_mov_b32_e32 v134, v4
	v_mov_b32_e32 v135, v4
	v_mov_b32_e32 v140, v4
	v_mov_b32_e32 v141, v4
	v_mov_b32_e32 v142, v4
	v_mov_b32_e32 v143, v4
	v_mov_b32_e32 v148, v4
	v_mov_b32_e32 v149, v4
	v_mov_b32_e32 v150, v4
	v_mov_b32_e32 v151, v4
	v_mov_b32_e32 v64, v4
	v_mov_b32_e32 v65, v4
	v_mov_b32_e32 v66, v4
	v_mov_b32_e32 v67, v4
	v_mov_b32_e32 v72, v4
	v_mov_b32_e32 v73, v4
	v_mov_b32_e32 v74, v4
	v_mov_b32_e32 v75, v4
	v_mov_b32_e32 v104, v4
	v_mov_b32_e32 v105, v4
	v_mov_b32_e32 v106, v4
	v_mov_b32_e32 v107, v4
	v_mov_b32_e32 v112, v4
	v_mov_b32_e32 v113, v4
	v_mov_b32_e32 v114, v4
	v_mov_b32_e32 v115, v4
	v_mov_b32_e32 v120, v4
	v_mov_b32_e32 v121, v4
	v_mov_b32_e32 v122, v4
	v_mov_b32_e32 v123, v4
	v_mov_b32_e32 v128, v4
	v_mov_b32_e32 v129, v4
	v_mov_b32_e32 v130, v4
	v_mov_b32_e32 v131, v4
	v_mov_b32_e32 v136, v4
	v_mov_b32_e32 v137, v4
	v_mov_b32_e32 v138, v4
	v_mov_b32_e32 v139, v4
	v_mov_b32_e32 v144, v4
	v_mov_b32_e32 v145, v4
	v_mov_b32_e32 v146, v4
	v_mov_b32_e32 v147, v4

; template <class Epi, class Sched, bool ALIGN_EPI = false, bool SP2 = false>
; __device__ __forceinline__ void gemm_phase(PG8_LAS unsigned char* lds, const Gemm g, const Sched& S, const Epi& E) {
;     ...
;         for (int t = 0; t < nt; t += 2) {
;     ...
; #pragma unroll
;         for (int a = 0; a < 2; ++a)
; #pragma unroll
;             for (int b = 0; b < 2; ++b)
; #pragma unroll
;                 for (int m = 0; m < 4; ++m)
; #pragma unroll
;                     for (int n = 0; n < 2; ++n) acc[a][b][m][n] = (f32x4){0.f, 0.f, 0.f, 0.f};
;         cur = nxt; cA = nA; cB = nB; ++ui;
.LBB0_838:
	s_andn2_b64 vcc, exec, s[18:19]
	s_cbranch_vccnz .LBB0_841
	s_add_u32 s10, s10, 0x80
	s_addc_u32 s11, s11, 0
	s_add_u32 s57, s34, 0x100
	v_mov_b32_e32 v4, 0
	s_addc_u32 s58, s35, 0
	s_mov_b32 s34, 0
	v_mov_b32_e32 v5, v4
	v_mov_b32_e32 v6, v4
	v_mov_b32_e32 v7, v4
	v_mov_b32_e32 v12, v4
	v_mov_b32_e32 v13, v4
	v_mov_b32_e32 v14, v4
	v_mov_b32_e32 v15, v4
	v_mov_b32_e32 v20, v4
	v_mov_b32_e32 v21, v4
	v_mov_b32_e32 v22, v4
	v_mov_b32_e32 v23, v4
	v_mov_b32_e32 v28, v4
	v_mov_b32_e32 v29, v4
	v_mov_b32_e32 v30, v4
	v_mov_b32_e32 v31, v4
	v_mov_b32_e32 v36, v4
	v_mov_b32_e32 v37, v4
	v_mov_b32_e32 v38, v4
	v_mov_b32_e32 v39, v4
	v_mov_b32_e32 v44, v4
	v_mov_b32_e32 v45, v4
	v_mov_b32_e32 v46, v4
	v_mov_b32_e32 v47, v4
	v_mov_b32_e32 v52, v4
	v_mov_b32_e32 v53, v4
	v_mov_b32_e32 v54, v4
	v_mov_b32_e32 v55, v4
	v_mov_b32_e32 v60, v4
	v_mov_b32_e32 v61, v4
	v_mov_b32_e32 v62, v4
	v_mov_b32_e32 v63, v4
	v_mov_b32_e32 v0, v4
	v_mov_b32_e32 v1, v4
	v_mov_b32_e32 v2, v4
	v_mov_b32_e32 v3, v4
	v_mov_b32_e32 v8, v4
	v_mov_b32_e32 v9, v4
	v_mov_b32_e32 v10, v4
	v_mov_b32_e32 v11, v4
	v_mov_b32_e32 v16, v4
	v_mov_b32_e32 v17, v4
	v_mov_b32_e32 v18, v4
	v_mov_b32_e32 v19, v4
	v_mov_b32_e32 v24, v4
	v_mov_b32_e32 v25, v4
	v_mov_b32_e32 v26, v4
	v_mov_b32_e32 v27, v4
	v_mov_b32_e32 v32, v4
	v_mov_b32_e32 v33, v4
	v_mov_b32_e32 v34, v4
	v_mov_b32_e32 v35, v4
	v_mov_b32_e32 v40, v4
	v_mov_b32_e32 v41, v4
	v_mov_b32_e32 v42, v4
	v_mov_b32_e32 v43, v4
	v_mov_b32_e32 v48, v4
	v_mov_b32_e32 v49, v4
	v_mov_b32_e32 v50, v4
	v_mov_b32_e32 v51, v4
	v_mov_b32_e32 v56, v4
	v_mov_b32_e32 v57, v4
	v_mov_b32_e32 v58, v4
	v_mov_b32_e32 v59, v4
	v_mov_b32_e32 v68, v4
	v_mov_b32_e32 v69, v4
	v_mov_b32_e32 v70, v4
	v_mov_b32_e32 v71, v4
	v_mov_b32_e32 v76, v4
	v_mov_b32_e32 v77, v4
	v_mov_b32_e32 v78, v4
	v_mov_b32_e32 v79, v4
	v_mov_b32_e32 v108, v4
	v_mov_b32_e32 v109, v4
	v_mov_b32_e32 v110, v4
	v_mov_b32_e32 v111, v4
	v_mov_b32_e32 v116, v4
	v_mov_b32_e32 v117, v4
	v_mov_b32_e32 v118, v4
	v_mov_b32_e32 v119, v4
	v_mov_b32_e32 v124, v4
	v_mov_b32_e32 v125, v4
	v_mov_b32_e32 v126, v4
	v_mov_b32_e32 v127, v4
	v_mov_b32_e32 v132, v4
	v_mov_b32_e32 v133, v4
	v_mov_b32_e32 v134, v4
	v_mov_b32_e32 v135, v4
	v_mov_b32_e32 v140, v4
	v_mov_b32_e32 v141, v4
	v_mov_b32_e32 v142, v4
	v_mov_b32_e32 v143, v4
	v_mov_b32_e32 v148, v4
	v_mov_b32_e32 v149, v4
	v_mov_b32_e32 v150, v4
	v_mov_b32_e32 v151, v4
	v_mov_b32_e32 v64, v4
	v_mov_b32_e32 v65, v4
	v_mov_b32_e32 v66, v4
	v_mov_b32_e32 v67, v4
	v_mov_b32_e32 v72, v4
	v_mov_b32_e32 v73, v4
	v_mov_b32_e32 v74, v4
	v_mov_b32_e32 v75, v4
	v_mov_b32_e32 v104, v4
	v_mov_b32_e32 v105, v4
	v_mov_b32_e32 v106, v4
	v_mov_b32_e32 v107, v4
	v_mov_b32_e32 v112, v4
	v_mov_b32_e32 v113, v4
	v_mov_b32_e32 v114, v4
	v_mov_b32_e32 v115, v4
	v_mov_b32_e32 v120, v4
	v_mov_b32_e32 v121, v4
	v_mov_b32_e32 v122, v4
	v_mov_b32_e32 v123, v4
	v_mov_b32_e32 v128, v4
	v_mov_b32_e32 v129, v4
	v_mov_b32_e32 v130, v4
	v_mov_b32_e32 v131, v4
	v_mov_b32_e32 v136, v4
	v_mov_b32_e32 v137, v4
	v_mov_b32_e32 v138, v4
	v_mov_b32_e32 v139, v4
	v_mov_b32_e32 v144, v4
	v_mov_b32_e32 v145, v4
	v_mov_b32_e32 v146, v4
	v_mov_b32_e32 v147, v4

; template <class Epi, class Sched, bool ALIGN_EPI = false, bool SP2 = false>
; __device__ __forceinline__ void gemm_phase(PG8_LAS unsigned char* lds, const Gemm g, const Sched& S, const Epi& E) {
;     ...
;         for (int t = 0; t < nt; t += 2) {
;     ...
; #pragma unroll
;         for (int a = 0; a < 2; ++a)
; #pragma unroll
;             for (int b = 0; b < 2; ++b)
; #pragma unroll
;                 for (int m = 0; m < 4; ++m)
; #pragma unroll
;                     for (int n = 0; n < 2; ++n) acc[a][b][m][n] = (f32x4){0.f, 0.f, 0.f, 0.f};
;         cur = nxt; cA = nA; cB = nB; ++ui;
.LBB0_901:
	s_andn2_b64 vcc, exec, s[16:17]
	s_cbranch_vccnz .LBB0_904
	s_add_u32 s4, s4, 0x80
	s_addc_u32 s5, s5, 0
	s_add_u32 s56, s28, 0x100
	v_mov_b32_e32 v4, 0
	s_addc_u32 s57, s29, 0
	s_mov_b32 s28, 0
	v_mov_b32_e32 v5, v4
	v_mov_b32_e32 v6, v4
	v_mov_b32_e32 v7, v4
	v_mov_b32_e32 v0, v4
	v_mov_b32_e32 v1, v4
	v_mov_b32_e32 v2, v4
	v_mov_b32_e32 v3, v4
	v_mov_b32_e32 v16, v4
	v_mov_b32_e32 v17, v4
	v_mov_b32_e32 v18, v4
	v_mov_b32_e32 v19, v4
	v_mov_b32_e32 v20, v4
	v_mov_b32_e32 v21, v4
	v_mov_b32_e32 v22, v4
	v_mov_b32_e32 v23, v4
	v_mov_b32_e32 v32, v4
	v_mov_b32_e32 v33, v4
	v_mov_b32_e32 v34, v4
	v_mov_b32_e32 v35, v4
	v_mov_b32_e32 v36, v4
	v_mov_b32_e32 v37, v4
	v_mov_b32_e32 v38, v4
	v_mov_b32_e32 v39, v4
	v_mov_b32_e32 v48, v4
	v_mov_b32_e32 v49, v4
	v_mov_b32_e32 v50, v4
	v_mov_b32_e32 v51, v4
	v_mov_b32_e32 v52, v4
	v_mov_b32_e32 v53, v4
	v_mov_b32_e32 v54, v4
	v_mov_b32_e32 v55, v4
	v_mov_b32_e32 v8, v4
	v_mov_b32_e32 v9, v4
	v_mov_b32_e32 v10, v4
	v_mov_b32_e32 v11, v4
	v_mov_b32_e32 v12, v4
	v_mov_b32_e32 v13, v4
	v_mov_b32_e32 v14, v4
	v_mov_b32_e32 v15, v4
	v_mov_b32_e32 v24, v4
	v_mov_b32_e32 v25, v4
	v_mov_b32_e32 v26, v4
	v_mov_b32_e32 v27, v4
	v_mov_b32_e32 v28, v4
	v_mov_b32_e32 v29, v4
	v_mov_b32_e32 v30, v4
	v_mov_b32_e32 v31, v4
	v_mov_b32_e32 v40, v4
	v_mov_b32_e32 v41, v4
	v_mov_b32_e32 v42, v4
	v_mov_b32_e32 v43, v4
	v_mov_b32_e32 v44, v4
	v_mov_b32_e32 v45, v4
	v_mov_b32_e32 v46, v4
	v_mov_b32_e32 v47, v4
	v_mov_b32_e32 v56, v4
	v_mov_b32_e32 v57, v4
	v_mov_b32_e32 v58, v4
	v_mov_b32_e32 v59, v4
	v_mov_b32_e32 v60, v4
	v_mov_b32_e32 v61, v4
	v_mov_b32_e32 v62, v4
	v_mov_b32_e32 v63, v4
	v_mov_b32_e32 v64, v4
	v_mov_b32_e32 v65, v4
	v_mov_b32_e32 v66, v4
	v_mov_b32_e32 v67, v4
	v_mov_b32_e32 v68, v4
	v_mov_b32_e32 v69, v4
	v_mov_b32_e32 v70, v4
	v_mov_b32_e32 v71, v4
	v_mov_b32_e32 v80, v4
	v_mov_b32_e32 v81, v4
	v_mov_b32_e32 v82, v4
	v_mov_b32_e32 v83, v4
	v_mov_b32_e32 v84, v4
	v_mov_b32_e32 v85, v4
	v_mov_b32_e32 v86, v4
	v_mov_b32_e32 v87, v4
	v_mov_b32_e32 v96, v4
	v_mov_b32_e32 v97, v4
	v_mov_b32_e32 v98, v4
	v_mov_b32_e32 v99, v4
	v_mov_b32_e32 v100, v4
	v_mov_b32_e32 v101, v4
	v_mov_b32_e32 v102, v4
	v_mov_b32_e32 v103, v4
	v_mov_b32_e32 v112, v4
	v_mov_b32_e32 v113, v4
	v_mov_b32_e32 v114, v4
	v_mov_b32_e32 v115, v4
	v_mov_b32_e32 v116, v4
	v_mov_b32_e32 v117, v4
	v_mov_b32_e32 v118, v4
	v_mov_b32_e32 v119, v4
	v_mov_b32_e32 v72, v4
	v_mov_b32_e32 v73, v4
	v_mov_b32_e32 v74, v4
	v_mov_b32_e32 v75, v4
	v_mov_b32_e32 v76, v4
	v_mov_b32_e32 v77, v4
	v_mov_b32_e32 v78, v4
	v_mov_b32_e32 v79, v4
	v_mov_b32_e32 v88, v4
	v_mov_b32_e32 v89, v4
	v_mov_b32_e32 v90, v4
	v_mov_b32_e32 v91, v4
	v_mov_b32_e32 v92, v4
	v_mov_b32_e32 v93, v4
	v_mov_b32_e32 v94, v4
	v_mov_b32_e32 v95, v4
	v_mov_b32_e32 v104, v4
	v_mov_b32_e32 v105, v4
	v_mov_b32_e32 v106, v4
	v_mov_b32_e32 v107, v4
	v_mov_b32_e32 v108, v4
	v_mov_b32_e32 v109, v4
	v_mov_b32_e32 v110, v4
	v_mov_b32_e32 v111, v4
	v_mov_b32_e32 v124, v4
	v_mov_b32_e32 v125, v4
	v_mov_b32_e32 v126, v4
	v_mov_b32_e32 v127, v4
	v_mov_b32_e32 v120, v4
	v_mov_b32_e32 v121, v4
	v_mov_b32_e32 v122, v4
	v_mov_b32_e32 v123, v4

; template <class Epi, class Sched, bool ALIGN_EPI = false, bool SP2 = false>
; __device__ __forceinline__ void gemm_phase(PG8_LAS unsigned char* lds, const Gemm g, const Sched& S, const Epi& E) {
;     ...
;         for (int t = 0; t < nt; t += 2) {
;     ...
; #pragma unroll
;         for (int a = 0; a < 2; ++a)
; #pragma unroll
;             for (int b = 0; b < 2; ++b)
; #pragma unroll
;                 for (int m = 0; m < 4; ++m)
; #pragma unroll
;                     for (int n = 0; n < 2; ++n) acc[a][b][m][n] = (f32x4){0.f, 0.f, 0.f, 0.f};
;         cur = nxt; cA = nA; cB = nB; ++ui;
.LBB0_1008:
	s_waitcnt vmcnt(0)
	s_andn2_b64 vcc, exec, s[20:21]
	s_cbranch_vccnz .LBB0_1011
	s_add_u32 s4, s4, 0x80
	s_addc_u32 s5, s5, 0
	s_add_u32 s11, s6, 0x100
	v_mov_b32_e32 v0, 0
	s_addc_u32 s29, s7, 0
	s_mov_b32 s6, 0
	v_mov_b32_e32 v1, v0
	v_mov_b32_e32 v2, v0
	v_mov_b32_e32 v3, v0
	v_mov_b32_e32 v4, v0
	v_mov_b32_e32 v5, v0
	v_mov_b32_e32 v6, v0
	v_mov_b32_e32 v7, v0
	v_mov_b32_e32 v16, v0
	v_mov_b32_e32 v17, v0
	v_mov_b32_e32 v18, v0
	v_mov_b32_e32 v19, v0
	v_mov_b32_e32 v20, v0
	v_mov_b32_e32 v21, v0
	v_mov_b32_e32 v22, v0
	v_mov_b32_e32 v23, v0
	v_mov_b32_e32 v32, v0
	v_mov_b32_e32 v33, v0
	v_mov_b32_e32 v34, v0
	v_mov_b32_e32 v35, v0
	v_mov_b32_e32 v36, v0
	v_mov_b32_e32 v37, v0
	v_mov_b32_e32 v38, v0
	v_mov_b32_e32 v39, v0
	v_mov_b32_e32 v48, v0
	v_mov_b32_e32 v49, v0
	v_mov_b32_e32 v50, v0
	v_mov_b32_e32 v51, v0
	v_mov_b32_e32 v52, v0
	v_mov_b32_e32 v53, v0
	v_mov_b32_e32 v54, v0
	v_mov_b32_e32 v55, v0
	v_mov_b32_e32 v8, v0
	v_mov_b32_e32 v9, v0
	v_mov_b32_e32 v10, v0
	v_mov_b32_e32 v11, v0
	v_mov_b32_e32 v12, v0
	v_mov_b32_e32 v13, v0
	v_mov_b32_e32 v14, v0
	v_mov_b32_e32 v15, v0
	v_mov_b32_e32 v24, v0
	v_mov_b32_e32 v25, v0
	v_mov_b32_e32 v26, v0
	v_mov_b32_e32 v27, v0
	v_mov_b32_e32 v28, v0
	v_mov_b32_e32 v29, v0
	v_mov_b32_e32 v30, v0
	v_mov_b32_e32 v31, v0
	v_mov_b32_e32 v40, v0
	v_mov_b32_e32 v41, v0
	v_mov_b32_e32 v42, v0
	v_mov_b32_e32 v43, v0
	v_mov_b32_e32 v44, v0
	v_mov_b32_e32 v45, v0
	v_mov_b32_e32 v46, v0
	v_mov_b32_e32 v47, v0
	v_mov_b32_e32 v56, v0
	v_mov_b32_e32 v57, v0
	v_mov_b32_e32 v58, v0
	v_mov_b32_e32 v59, v0
	v_mov_b32_e32 v60, v0
	v_mov_b32_e32 v61, v0
	v_mov_b32_e32 v62, v0
	v_mov_b32_e32 v63, v0
	v_mov_b32_e32 v64, v0
	v_mov_b32_e32 v65, v0
	v_mov_b32_e32 v66, v0
	v_mov_b32_e32 v67, v0
	v_mov_b32_e32 v68, v0
	v_mov_b32_e32 v69, v0
	v_mov_b32_e32 v70, v0
	v_mov_b32_e32 v71, v0
	v_mov_b32_e32 v80, v0
	v_mov_b32_e32 v81, v0
	v_mov_b32_e32 v82, v0
	v_mov_b32_e32 v83, v0
	v_mov_b32_e32 v84, v0
	v_mov_b32_e32 v85, v0
	v_mov_b32_e32 v86, v0
	v_mov_b32_e32 v87, v0
	v_mov_b32_e32 v96, v0
	v_mov_b32_e32 v97, v0
	v_mov_b32_e32 v98, v0
	v_mov_b32_e32 v99, v0
	v_mov_b32_e32 v100, v0
	v_mov_b32_e32 v101, v0
	v_mov_b32_e32 v102, v0
	v_mov_b32_e32 v103, v0
	v_mov_b32_e32 v112, v0
	v_mov_b32_e32 v113, v0
	v_mov_b32_e32 v114, v0
	v_mov_b32_e32 v115, v0
	v_mov_b32_e32 v116, v0
	v_mov_b32_e32 v117, v0
	v_mov_b32_e32 v118, v0
	v_mov_b32_e32 v119, v0
	v_mov_b32_e32 v72, v0
	v_mov_b32_e32 v73, v0
	v_mov_b32_e32 v74, v0
	v_mov_b32_e32 v75, v0
	v_mov_b32_e32 v76, v0
	v_mov_b32_e32 v77, v0
	v_mov_b32_e32 v78, v0
	v_mov_b32_e32 v79, v0
	v_mov_b32_e32 v88, v0
	v_mov_b32_e32 v89, v0
	v_mov_b32_e32 v90, v0
	v_mov_b32_e32 v91, v0
	v_mov_b32_e32 v92, v0
	v_mov_b32_e32 v93, v0
	v_mov_b32_e32 v94, v0
	v_mov_b32_e32 v95, v0
	v_mov_b32_e32 v104, v0
	v_mov_b32_e32 v105, v0
	v_mov_b32_e32 v106, v0
	v_mov_b32_e32 v107, v0
	v_mov_b32_e32 v108, v0
	v_mov_b32_e32 v109, v0
	v_mov_b32_e32 v110, v0
	v_mov_b32_e32 v111, v0
	v_mov_b32_e32 v120, v0
	v_mov_b32_e32 v121, v0
	v_mov_b32_e32 v122, v0
	v_mov_b32_e32 v123, v0
	v_mov_b32_e32 v124, v0
	v_mov_b32_e32 v125, v0
	v_mov_b32_e32 v126, v0
	v_mov_b32_e32 v127, v0

; template <class Epi, class Sched, bool ALIGN_EPI = false, bool SP2 = false>
; __device__ __forceinline__ void gemm_phase(PG8_LAS unsigned char* lds, const Gemm g, const Sched& S, const Epi& E) {
;     ...
;         for (int t = 0; t < nt; t += 2) {
;     ...
; #pragma unroll
;         for (int a = 0; a < 2; ++a)
; #pragma unroll
;             for (int b = 0; b < 2; ++b)
; #pragma unroll
;                 for (int m = 0; m < 4; ++m)
; #pragma unroll
;                     for (int n = 0; n < 2; ++n) acc[a][b][m][n] = (f32x4){0.f, 0.f, 0.f, 0.f};
;         cur = nxt; cA = nA; cB = nB; ++ui;
.LBB0_1395:
	s_andn2_b64 vcc, exec, s[14:15]
	s_cbranch_vccnz .LBB0_1398
	s_add_u32 s20, s20, 0x80
	s_addc_u32 s21, s21, 0
	s_add_u32 s50, s22, 0x100
	v_mov_b32_e32 v0, 0
	s_addc_u32 s51, s23, 0
	s_mov_b32 s22, 0
	v_mov_b32_e32 v1, v0
	v_mov_b32_e32 v2, v0
	v_mov_b32_e32 v3, v0
	v_mov_b32_e32 v4, v0
	v_mov_b32_e32 v5, v0
	v_mov_b32_e32 v6, v0
	v_mov_b32_e32 v7, v0
	v_mov_b32_e32 v16, v0
	v_mov_b32_e32 v17, v0
	v_mov_b32_e32 v18, v0
	v_mov_b32_e32 v19, v0
	v_mov_b32_e32 v20, v0
	v_mov_b32_e32 v21, v0
	v_mov_b32_e32 v22, v0
	v_mov_b32_e32 v23, v0
	v_mov_b32_e32 v32, v0
	v_mov_b32_e32 v33, v0
	v_mov_b32_e32 v34, v0
	v_mov_b32_e32 v35, v0
	v_mov_b32_e32 v36, v0
	v_mov_b32_e32 v37, v0
	v_mov_b32_e32 v38, v0
	v_mov_b32_e32 v39, v0
	v_mov_b32_e32 v48, v0
	v_mov_b32_e32 v49, v0
	v_mov_b32_e32 v50, v0
	v_mov_b32_e32 v51, v0
	v_mov_b32_e32 v52, v0
	v_mov_b32_e32 v53, v0
	v_mov_b32_e32 v54, v0
	v_mov_b32_e32 v55, v0
	v_mov_b32_e32 v8, v0
	v_mov_b32_e32 v9, v0
	v_mov_b32_e32 v10, v0
	v_mov_b32_e32 v11, v0
	v_mov_b32_e32 v12, v0
	v_mov_b32_e32 v13, v0
	v_mov_b32_e32 v14, v0
	v_mov_b32_e32 v15, v0
	v_mov_b32_e32 v24, v0
	v_mov_b32_e32 v25, v0
	v_mov_b32_e32 v26, v0
	v_mov_b32_e32 v27, v0
	v_mov_b32_e32 v28, v0
	v_mov_b32_e32 v29, v0
	v_mov_b32_e32 v30, v0
	v_mov_b32_e32 v31, v0
	v_mov_b32_e32 v40, v0
	v_mov_b32_e32 v41, v0
	v_mov_b32_e32 v42, v0
	v_mov_b32_e32 v43, v0
	v_mov_b32_e32 v44, v0
	v_mov_b32_e32 v45, v0
	v_mov_b32_e32 v46, v0
	v_mov_b32_e32 v47, v0
	v_mov_b32_e32 v56, v0
	v_mov_b32_e32 v57, v0
	v_mov_b32_e32 v58, v0
	v_mov_b32_e32 v59, v0
	v_mov_b32_e32 v60, v0
	v_mov_b32_e32 v61, v0
	v_mov_b32_e32 v62, v0
	v_mov_b32_e32 v63, v0
	v_mov_b32_e32 v64, v0
	v_mov_b32_e32 v65, v0
	v_mov_b32_e32 v66, v0
	v_mov_b32_e32 v67, v0
	v_mov_b32_e32 v68, v0
	v_mov_b32_e32 v69, v0
	v_mov_b32_e32 v70, v0
	v_mov_b32_e32 v71, v0
	v_mov_b32_e32 v80, v0
	v_mov_b32_e32 v81, v0
	v_mov_b32_e32 v82, v0
	v_mov_b32_e32 v83, v0
	v_mov_b32_e32 v84, v0
	v_mov_b32_e32 v85, v0
	v_mov_b32_e32 v86, v0
	v_mov_b32_e32 v87, v0
	v_mov_b32_e32 v96, v0
	v_mov_b32_e32 v97, v0
	v_mov_b32_e32 v98, v0
	v_mov_b32_e32 v99, v0
	v_mov_b32_e32 v100, v0
	v_mov_b32_e32 v101, v0
	v_mov_b32_e32 v102, v0
	v_mov_b32_e32 v103, v0
	v_mov_b32_e32 v112, v0
	v_mov_b32_e32 v113, v0
	v_mov_b32_e32 v114, v0
	v_mov_b32_e32 v115, v0
	v_mov_b32_e32 v116, v0
	v_mov_b32_e32 v117, v0
	v_mov_b32_e32 v118, v0
	v_mov_b32_e32 v119, v0
	v_mov_b32_e32 v72, v0
	v_mov_b32_e32 v73, v0
	v_mov_b32_e32 v74, v0
	v_mov_b32_e32 v75, v0
	v_mov_b32_e32 v76, v0
	v_mov_b32_e32 v77, v0
	v_mov_b32_e32 v78, v0
	v_mov_b32_e32 v79, v0
	v_mov_b32_e32 v88, v0
	v_mov_b32_e32 v89, v0
	v_mov_b32_e32 v90, v0
	v_mov_b32_e32 v91, v0
	v_mov_b32_e32 v92, v0
	v_mov_b32_e32 v93, v0
	v_mov_b32_e32 v94, v0
	v_mov_b32_e32 v95, v0
	v_mov_b32_e32 v104, v0
	v_mov_b32_e32 v105, v0
	v_mov_b32_e32 v106, v0
	v_mov_b32_e32 v107, v0
	v_mov_b32_e32 v108, v0
	v_mov_b32_e32 v109, v0
	v_mov_b32_e32 v110, v0
	v_mov_b32_e32 v111, v0
	v_mov_b32_e32 v124, v0
	v_mov_b32_e32 v125, v0
	v_mov_b32_e32 v126, v0
	v_mov_b32_e32 v127, v0
	v_mov_b32_e32 v120, v0
	v_mov_b32_e32 v121, v0
	v_mov_b32_e32 v122, v0
	v_mov_b32_e32 v123, v0
